# v53 plus final RMSNorm phase pipelined: 3 rows in flight, counted vmcnt, DPP+readlane wave sum (epilogue de-serialisation)
# speedup vs baseline: 1.0049x; 1.0049x over previous
; __device__ __forceinline__ int opaque_tid() { int t = threadIdx.x; asm volatile("" : "+v"(t)); return t; }
; __device__ __forceinline__ void phase_final_norm(float* x, const float* g) {
;     const int tid = opaque_tid(), lane = tid & 63, wave = tid >> 6;
;     const int gw = blockIdx.x * NWAVES + wave, NGW = gridDim.x * NWAVES;
;     constexpr int NR = 4;
;     f32x4 gg[4];
; #pragma unroll
;     for (int j = 0; j < 4; ++j) gg[j] = ((const f32x4*)g)[lane + 64 * j];
;     for (int m0 = gw; m0 < M; m0 += NR * NGW) {
;         f32x4 v[NR][4];
; #pragma unroll
;         for (int r = 0; r < NR; ++r) { const int m = (m0 + r * NGW < M ? m0 + r * NGW : m0); const f32x4* xr = (const f32x4*)(x + (size_t)m * D) + lane;
; #pragma unroll
;             for (int j = 0; j < 4; ++j) v[r][j] = xr[64 * j]; }
; #pragma unroll
;         for (int r = 0; r < NR; ++r) { const int m = m0 + r * NGW; if (m < M) {
;             float s = 0.f;
; #pragma unroll
;             for (int j = 0; j < 4; ++j) s += (v[r][j].x * v[r][j].x + v[r][j].y * v[r][j].y) + (v[r][j].z * v[r][j].z + v[r][j].w * v[r][j].w);
;             const float rstd = 1.0f / sqrtf(wave_sum(s) * (1.f / D) + 1e-6f);
;             f32x4* xr = (f32x4*)(x + (size_t)m * D) + lane;
; #pragma unroll
;             for (int j = 0; j < 4; ++j) xr[64 * j] = v[r][j] * rstd * gg[j]; } }
;     }
.LBB0_2424:
	s_cmp_lt_i32 s90, 16
	s_cselect_b64 s[2:3], -1, 0
	s_and_b64 s[0:1], s[2:3], s[0:1]
	s_andn2_b64 vcc, exec, s[0:1]
	s_cbranch_vccnz .LBB0_2434
	v_lshrrev_b32_e32 v176, 6, v180
	v_and_b32_e32 v177, 63, v180
	v_readfirstlane_b32 s0, v176
	v_lshlrev_b32_e32 v176, 4, v177
	v_mov_b32_e32 v170, 0x358637bd
	v_mov_b32_e32 v171, 0x260
	v_mov_b32_e32 v178, 0xf800000
	global_load_dwordx4 v[128:131], v176, s[84:85]
	global_load_dwordx4 v[132:135], v176, s[84:85] offset:1024
	global_load_dwordx4 v[136:139], v176, s[84:85] offset:2048
	global_load_dwordx4 v[140:143], v176, s[84:85] offset:3072
	s_lshl_b32 s1, s24, 3
	s_add_i32 s0, s0, s1
	s_lshl_b32 s2, s28, 3
	s_mul_i32 s1, s2, 3
	s_mov_b32 s18, s0
	s_add_i32 s19, s0, s2
	s_add_i32 s20, s19, s2
	s_cmp_lt_u32 s0, 0x10000
	s_cbranch_scc0 .LNf_done
	s_cmp_lt_u32 s18, 0x10000
	s_cselect_b32 s3, s18, s0
	s_lshl_b32 s4, s3, 12
	s_add_u32 s6, s86, s4
	s_addc_u32 s7, s87, 0
	global_load_dwordx4 v[0:3], v176, s[6:7]
	global_load_dwordx4 v[4:7], v176, s[6:7] offset:1024
	global_load_dwordx4 v[8:11], v176, s[6:7] offset:2048
	global_load_dwordx4 v[12:15], v176, s[6:7] offset:3072
	s_cmp_lt_u32 s19, 0x10000
	s_cselect_b32 s3, s19, s0
	s_lshl_b32 s4, s3, 12
	s_add_u32 s6, s86, s4
	s_addc_u32 s7, s87, 0
	global_load_dwordx4 v[16:19], v176, s[6:7]
	global_load_dwordx4 v[20:23], v176, s[6:7] offset:1024
	global_load_dwordx4 v[24:27], v176, s[6:7] offset:2048
	global_load_dwordx4 v[28:31], v176, s[6:7] offset:3072
	s_cmp_lt_u32 s20, 0x10000
	s_cselect_b32 s3, s20, s0
	s_lshl_b32 s4, s3, 12
	s_add_u32 s6, s86, s4
	s_addc_u32 s7, s87, 0
	global_load_dwordx4 v[32:35], v176, s[6:7]
	global_load_dwordx4 v[36:39], v176, s[6:7] offset:1024
	global_load_dwordx4 v[40:43], v176, s[6:7] offset:2048
	global_load_dwordx4 v[44:47], v176, s[6:7] offset:3072
	s_waitcnt vmcnt(8)
.LNf_loop:
	s_cmp_lt_u32 s18, 0x10000
	s_cbranch_scc0 .LNf_done
	s_waitcnt vmcnt(12)
	v_pk_mul_f32 v[172:173], v[0:1], v[0:1]
	v_pk_mul_f32 v[174:175], v[2:3], v[2:3]
	v_pk_fma_f32 v[172:173], v[4:5], v[4:5], v[172:173]
	v_pk_fma_f32 v[174:175], v[6:7], v[6:7], v[174:175]
	v_pk_fma_f32 v[172:173], v[8:9], v[8:9], v[172:173]
	v_pk_fma_f32 v[174:175], v[10:11], v[10:11], v[174:175]
	v_pk_fma_f32 v[172:173], v[12:13], v[12:13], v[172:173]
	v_pk_fma_f32 v[174:175], v[14:15], v[14:15], v[174:175]
	v_pk_add_f32 v[172:173], v[172:173], v[174:175]
	s_lshl_b32 s4, s18, 12
	v_add_f32_e32 v160, v172, v173
	s_add_u32 s16, s86, s4
	s_addc_u32 s17, s87, 0
	s_nop 1
	v_add_f32_dpp v160, v160, v160 quad_perm:[1,0,3,2] row_mask:0xf bank_mask:0xf bound_ctrl:1
	s_nop 1
	v_add_f32_dpp v160, v160, v160 quad_perm:[2,3,0,1] row_mask:0xf bank_mask:0xf bound_ctrl:1
	s_nop 1
	v_add_f32_dpp v160, v160, v160 row_half_mirror row_mask:0xf bank_mask:0xf bound_ctrl:1
	s_nop 1
	v_add_f32_dpp v160, v160, v160 row_mirror row_mask:0xf bank_mask:0xf bound_ctrl:1
	s_nop 0
	v_readlane_b32 s4, v160, 0
	v_readlane_b32 s5, v160, 16
	v_readlane_b32 s3, v160, 32
	s_nop 1
	v_mov_b32_e32 v161, s4
	v_add_f32_e32 v161, s5, v161
	v_readlane_b32 s4, v160, 48
	v_add_f32_e32 v161, s3, v161
	s_nop 1
	v_add_f32_e32 v160, s4, v161
	v_fmamk_f32 v160, v160, 0x3a800000, v170
	v_mul_f32_e32 v161, 0x4f800000, v160
	v_cmp_gt_f32_e32 vcc, v178, v160
	s_nop 1
	v_cndmask_b32_e32 v162, v160, v161, vcc
	v_sqrt_f32_e32 v164, v162
	s_nop 0
	v_add_u32_e32 v165, -1, v164
	v_add_u32_e32 v166, 1, v164
	v_fma_f32 v167, -v165, v164, v162
	v_fma_f32 v168, -v166, v164, v162
	v_cmp_ge_f32_e64 s[4:5], 0, v167
	s_nop 1
	v_cndmask_b32_e64 v164, v164, v165, s[4:5]
	v_cmp_lt_f32_e64 s[4:5], 0, v168
	s_nop 1
	v_cndmask_b32_e64 v164, v164, v166, s[4:5]
	v_mul_f32_e32 v165, 0x37800000, v164
	v_cndmask_b32_e32 v164, v164, v165, vcc
	v_cmp_class_f32_e32 vcc, v162, v171
	s_nop 1
	v_cndmask_b32_e32 v162, v164, v162, vcc
	v_div_scale_f32 v164, s[4:5], v162, v162, 1.0
	v_rcp_f32_e32 v165, v164
	v_div_scale_f32 v166, vcc, 1.0, v162, 1.0
	v_fma_f32 v167, -v164, v165, 1.0
	v_fmac_f32_e32 v165, v167, v165
	v_mul_f32_e32 v167, v166, v165
	v_fma_f32 v168, -v164, v167, v166
	v_fmac_f32_e32 v167, v168, v165
	v_fma_f32 v164, -v164, v167, v166
	v_div_fmas_f32 v164, v164, v165, v167
	v_div_fixup_f32 v162, v164, v162, 1.0
	v_pk_mul_f32 v[0:1], v[0:1], v[162:163] op_sel_hi:[1,0]
	v_pk_mul_f32 v[2:3], v[2:3], v[162:163] op_sel_hi:[1,0]
	v_pk_mul_f32 v[4:5], v[4:5], v[162:163] op_sel_hi:[1,0]
	v_pk_mul_f32 v[6:7], v[6:7], v[162:163] op_sel_hi:[1,0]
	v_pk_mul_f32 v[8:9], v[8:9], v[162:163] op_sel_hi:[1,0]
	v_pk_mul_f32 v[10:11], v[10:11], v[162:163] op_sel_hi:[1,0]
	v_pk_mul_f32 v[12:13], v[12:13], v[162:163] op_sel_hi:[1,0]
	v_pk_mul_f32 v[14:15], v[14:15], v[162:163] op_sel_hi:[1,0]
	v_pk_mul_f32 v[0:1], v[128:129], v[0:1]
	v_pk_mul_f32 v[2:3], v[130:131], v[2:3]
	v_pk_mul_f32 v[4:5], v[132:133], v[4:5]
	v_pk_mul_f32 v[6:7], v[134:135], v[6:7]
	v_pk_mul_f32 v[8:9], v[136:137], v[8:9]
	v_pk_mul_f32 v[10:11], v[138:139], v[10:11]
	v_pk_mul_f32 v[12:13], v[140:141], v[12:13]
	v_pk_mul_f32 v[14:15], v[142:143], v[14:15]
	global_store_dwordx4 v176, v[0:3], s[16:17]
	global_store_dwordx4 v176, v[4:7], s[16:17] offset:1024
	global_store_dwordx4 v176, v[8:11], s[16:17] offset:2048
	global_store_dwordx4 v176, v[12:15], s[16:17] offset:3072
	s_add_i32 s18, s18, s1
	s_cmp_lt_u32 s18, 0x10000
	s_cselect_b32 s3, s18, s0
	s_lshl_b32 s4, s3, 12
	s_add_u32 s6, s86, s4
	s_addc_u32 s7, s87, 0
	global_load_dwordx4 v[0:3], v176, s[6:7]
	global_load_dwordx4 v[4:7], v176, s[6:7] offset:1024
	global_load_dwordx4 v[8:11], v176, s[6:7] offset:2048
	global_load_dwordx4 v[12:15], v176, s[6:7] offset:3072
	s_cmp_lt_u32 s19, 0x10000
	s_cbranch_scc0 .LNf_done
; __device__ __forceinline__ void phase_final_norm(float* x, const float* g) {
;     ...
;         for (int r = 0; r < NR; ++r) { const int m = (m0 + r * NGW < M ? m0 + r * NGW : m0); const f32x4* xr = (const f32x4*)(x + (size_t)m * D) + lane;
; #pragma unroll
;             for (int j = 0; j < 4; ++j) v[r][j] = xr[64 * j]; }
; #pragma unroll
;         for (int r = 0; r < NR; ++r) { const int m = m0 + r * NGW; if (m < M) {
;             float s = 0.f;
; #pragma unroll
;             for (int j = 0; j < 4; ++j) s += (v[r][j].x * v[r][j].x + v[r][j].y * v[r][j].y) + (v[r][j].z * v[r][j].z + v[r][j].w * v[r][j].w);
;             const float rstd = 1.0f / sqrtf(wave_sum(s) * (1.f / D) + 1e-6f);
;             f32x4* xr = (f32x4*)(x + (size_t)m * D) + lane;
; #pragma unroll
;             for (int j = 0; j < 4; ++j) xr[64 * j] = v[r][j] * rstd * gg[j]; } }
	s_waitcnt vmcnt(12)
	v_pk_mul_f32 v[172:173], v[16:17], v[16:17]
	v_pk_mul_f32 v[174:175], v[18:19], v[18:19]
	v_pk_fma_f32 v[172:173], v[20:21], v[20:21], v[172:173]
	v_pk_fma_f32 v[174:175], v[22:23], v[22:23], v[174:175]
	v_pk_fma_f32 v[172:173], v[24:25], v[24:25], v[172:173]
	v_pk_fma_f32 v[174:175], v[26:27], v[26:27], v[174:175]
	v_pk_fma_f32 v[172:173], v[28:29], v[28:29], v[172:173]
	v_pk_fma_f32 v[174:175], v[30:31], v[30:31], v[174:175]
	v_pk_add_f32 v[172:173], v[172:173], v[174:175]
	s_lshl_b32 s4, s19, 12
	v_add_f32_e32 v160, v172, v173
	s_add_u32 s16, s86, s4
	s_addc_u32 s17, s87, 0
	s_nop 1
	v_add_f32_dpp v160, v160, v160 quad_perm:[1,0,3,2] row_mask:0xf bank_mask:0xf bound_ctrl:1
	s_nop 1
	v_add_f32_dpp v160, v160, v160 quad_perm:[2,3,0,1] row_mask:0xf bank_mask:0xf bound_ctrl:1
	s_nop 1
	v_add_f32_dpp v160, v160, v160 row_half_mirror row_mask:0xf bank_mask:0xf bound_ctrl:1
	s_nop 1
	v_add_f32_dpp v160, v160, v160 row_mirror row_mask:0xf bank_mask:0xf bound_ctrl:1
	s_nop 0
	v_readlane_b32 s4, v160, 0
	v_readlane_b32 s5, v160, 16
	v_readlane_b32 s3, v160, 32
	s_nop 1
	v_mov_b32_e32 v161, s4
	v_add_f32_e32 v161, s5, v161
	v_readlane_b32 s4, v160, 48
	v_add_f32_e32 v161, s3, v161
	s_nop 1
	v_add_f32_e32 v160, s4, v161
	v_fmamk_f32 v160, v160, 0x3a800000, v170
	v_mul_f32_e32 v161, 0x4f800000, v160
	v_cmp_gt_f32_e32 vcc, v178, v160
	s_nop 1
	v_cndmask_b32_e32 v162, v160, v161, vcc
	v_sqrt_f32_e32 v164, v162
	s_nop 0
	v_add_u32_e32 v165, -1, v164
	v_add_u32_e32 v166, 1, v164
	v_fma_f32 v167, -v165, v164, v162
	v_fma_f32 v168, -v166, v164, v162
	v_cmp_ge_f32_e64 s[4:5], 0, v167
	s_nop 1
	v_cndmask_b32_e64 v164, v164, v165, s[4:5]
	v_cmp_lt_f32_e64 s[4:5], 0, v168
	s_nop 1
	v_cndmask_b32_e64 v164, v164, v166, s[4:5]
	v_mul_f32_e32 v165, 0x37800000, v164
	v_cndmask_b32_e32 v164, v164, v165, vcc
	v_cmp_class_f32_e32 vcc, v162, v171
	s_nop 1
	v_cndmask_b32_e32 v162, v164, v162, vcc
	v_div_scale_f32 v164, s[4:5], v162, v162, 1.0
	v_rcp_f32_e32 v165, v164
	v_div_scale_f32 v166, vcc, 1.0, v162, 1.0
	v_fma_f32 v167, -v164, v165, 1.0
	v_fmac_f32_e32 v165, v167, v165
	v_mul_f32_e32 v167, v166, v165
	v_fma_f32 v168, -v164, v167, v166
	v_fmac_f32_e32 v167, v168, v165
	v_fma_f32 v164, -v164, v167, v166
	v_div_fmas_f32 v164, v164, v165, v167
	v_div_fixup_f32 v162, v164, v162, 1.0
	v_pk_mul_f32 v[16:17], v[16:17], v[162:163] op_sel_hi:[1,0]
	v_pk_mul_f32 v[18:19], v[18:19], v[162:163] op_sel_hi:[1,0]
	v_pk_mul_f32 v[20:21], v[20:21], v[162:163] op_sel_hi:[1,0]
	v_pk_mul_f32 v[22:23], v[22:23], v[162:163] op_sel_hi:[1,0]
	v_pk_mul_f32 v[24:25], v[24:25], v[162:163] op_sel_hi:[1,0]
	v_pk_mul_f32 v[26:27], v[26:27], v[162:163] op_sel_hi:[1,0]
	v_pk_mul_f32 v[28:29], v[28:29], v[162:163] op_sel_hi:[1,0]
	v_pk_mul_f32 v[30:31], v[30:31], v[162:163] op_sel_hi:[1,0]
	v_pk_mul_f32 v[16:17], v[128:129], v[16:17]
	v_pk_mul_f32 v[18:19], v[130:131], v[18:19]
	v_pk_mul_f32 v[20:21], v[132:133], v[20:21]
	v_pk_mul_f32 v[22:23], v[134:135], v[22:23]
	v_pk_mul_f32 v[24:25], v[136:137], v[24:25]
	v_pk_mul_f32 v[26:27], v[138:139], v[26:27]
	v_pk_mul_f32 v[28:29], v[140:141], v[28:29]
	v_pk_mul_f32 v[30:31], v[142:143], v[30:31]
	global_store_dwordx4 v176, v[16:19], s[16:17]
	global_store_dwordx4 v176, v[20:23], s[16:17] offset:1024
	global_store_dwordx4 v176, v[24:27], s[16:17] offset:2048
	global_store_dwordx4 v176, v[28:31], s[16:17] offset:3072
	s_add_i32 s19, s19, s1
	s_cmp_lt_u32 s19, 0x10000
	s_cselect_b32 s3, s19, s0
	s_lshl_b32 s4, s3, 12
	s_add_u32 s6, s86, s4
	s_addc_u32 s7, s87, 0
	global_load_dwordx4 v[16:19], v176, s[6:7]
	global_load_dwordx4 v[20:23], v176, s[6:7] offset:1024
	global_load_dwordx4 v[24:27], v176, s[6:7] offset:2048
	global_load_dwordx4 v[28:31], v176, s[6:7] offset:3072
	s_cmp_lt_u32 s20, 0x10000
	s_cbranch_scc0 .LNf_done
; __device__ __forceinline__ void phase_final_norm(float* x, const float* g) {
;     ...
;         for (int r = 0; r < NR; ++r) { const int m = (m0 + r * NGW < M ? m0 + r * NGW : m0); const f32x4* xr = (const f32x4*)(x + (size_t)m * D) + lane;
; #pragma unroll
;             for (int j = 0; j < 4; ++j) v[r][j] = xr[64 * j]; }
; #pragma unroll
;         for (int r = 0; r < NR; ++r) { const int m = m0 + r * NGW; if (m < M) {
;             float s = 0.f;
; #pragma unroll
;             for (int j = 0; j < 4; ++j) s += (v[r][j].x * v[r][j].x + v[r][j].y * v[r][j].y) + (v[r][j].z * v[r][j].z + v[r][j].w * v[r][j].w);
;             const float rstd = 1.0f / sqrtf(wave_sum(s) * (1.f / D) + 1e-6f);
;             f32x4* xr = (f32x4*)(x + (size_t)m * D) + lane;
; #pragma unroll
;             for (int j = 0; j < 4; ++j) xr[64 * j] = v[r][j] * rstd * gg[j]; } }
	s_waitcnt vmcnt(12)
	v_pk_mul_f32 v[172:173], v[32:33], v[32:33]
	v_pk_mul_f32 v[174:175], v[34:35], v[34:35]
	v_pk_fma_f32 v[172:173], v[36:37], v[36:37], v[172:173]
	v_pk_fma_f32 v[174:175], v[38:39], v[38:39], v[174:175]
	v_pk_fma_f32 v[172:173], v[40:41], v[40:41], v[172:173]
	v_pk_fma_f32 v[174:175], v[42:43], v[42:43], v[174:175]
	v_pk_fma_f32 v[172:173], v[44:45], v[44:45], v[172:173]
	v_pk_fma_f32 v[174:175], v[46:47], v[46:47], v[174:175]
	v_pk_add_f32 v[172:173], v[172:173], v[174:175]
	s_lshl_b32 s4, s20, 12
	v_add_f32_e32 v160, v172, v173
	s_add_u32 s16, s86, s4
	s_addc_u32 s17, s87, 0
	s_nop 1
	v_add_f32_dpp v160, v160, v160 quad_perm:[1,0,3,2] row_mask:0xf bank_mask:0xf bound_ctrl:1
	s_nop 1
	v_add_f32_dpp v160, v160, v160 quad_perm:[2,3,0,1] row_mask:0xf bank_mask:0xf bound_ctrl:1
	s_nop 1
	v_add_f32_dpp v160, v160, v160 row_half_mirror row_mask:0xf bank_mask:0xf bound_ctrl:1
	s_nop 1
	v_add_f32_dpp v160, v160, v160 row_mirror row_mask:0xf bank_mask:0xf bound_ctrl:1
	s_nop 0
	v_readlane_b32 s4, v160, 0
	v_readlane_b32 s5, v160, 16
	v_readlane_b32 s3, v160, 32
	s_nop 1
	v_mov_b32_e32 v161, s4
	v_add_f32_e32 v161, s5, v161
	v_readlane_b32 s4, v160, 48
	v_add_f32_e32 v161, s3, v161
	s_nop 1
	v_add_f32_e32 v160, s4, v161
	v_fmamk_f32 v160, v160, 0x3a800000, v170
	v_mul_f32_e32 v161, 0x4f800000, v160
	v_cmp_gt_f32_e32 vcc, v178, v160
	s_nop 1
	v_cndmask_b32_e32 v162, v160, v161, vcc
	v_sqrt_f32_e32 v164, v162
	s_nop 0
	v_add_u32_e32 v165, -1, v164
	v_add_u32_e32 v166, 1, v164
	v_fma_f32 v167, -v165, v164, v162
	v_fma_f32 v168, -v166, v164, v162
	v_cmp_ge_f32_e64 s[4:5], 0, v167
	s_nop 1
	v_cndmask_b32_e64 v164, v164, v165, s[4:5]
	v_cmp_lt_f32_e64 s[4:5], 0, v168
	s_nop 1
	v_cndmask_b32_e64 v164, v164, v166, s[4:5]
	v_mul_f32_e32 v165, 0x37800000, v164
	v_cndmask_b32_e32 v164, v164, v165, vcc
	v_cmp_class_f32_e32 vcc, v162, v171
	s_nop 1
	v_cndmask_b32_e32 v162, v164, v162, vcc
	v_div_scale_f32 v164, s[4:5], v162, v162, 1.0
	v_rcp_f32_e32 v165, v164
	v_div_scale_f32 v166, vcc, 1.0, v162, 1.0
	v_fma_f32 v167, -v164, v165, 1.0
	v_fmac_f32_e32 v165, v167, v165
	v_mul_f32_e32 v167, v166, v165
	v_fma_f32 v168, -v164, v167, v166
	v_fmac_f32_e32 v167, v168, v165
	v_fma_f32 v164, -v164, v167, v166
	v_div_fmas_f32 v164, v164, v165, v167
	v_div_fixup_f32 v162, v164, v162, 1.0
	v_pk_mul_f32 v[32:33], v[32:33], v[162:163] op_sel_hi:[1,0]
	v_pk_mul_f32 v[34:35], v[34:35], v[162:163] op_sel_hi:[1,0]
	v_pk_mul_f32 v[36:37], v[36:37], v[162:163] op_sel_hi:[1,0]
	v_pk_mul_f32 v[38:39], v[38:39], v[162:163] op_sel_hi:[1,0]
	v_pk_mul_f32 v[40:41], v[40:41], v[162:163] op_sel_hi:[1,0]
	v_pk_mul_f32 v[42:43], v[42:43], v[162:163] op_sel_hi:[1,0]
	v_pk_mul_f32 v[44:45], v[44:45], v[162:163] op_sel_hi:[1,0]
	v_pk_mul_f32 v[46:47], v[46:47], v[162:163] op_sel_hi:[1,0]
	v_pk_mul_f32 v[32:33], v[128:129], v[32:33]
	v_pk_mul_f32 v[34:35], v[130:131], v[34:35]
	v_pk_mul_f32 v[36:37], v[132:133], v[36:37]
	v_pk_mul_f32 v[38:39], v[134:135], v[38:39]
	v_pk_mul_f32 v[40:41], v[136:137], v[40:41]
	v_pk_mul_f32 v[42:43], v[138:139], v[42:43]
	v_pk_mul_f32 v[44:45], v[140:141], v[44:45]
	v_pk_mul_f32 v[46:47], v[142:143], v[46:47]
	global_store_dwordx4 v176, v[32:35], s[16:17]
	global_store_dwordx4 v176, v[36:39], s[16:17] offset:1024
	global_store_dwordx4 v176, v[40:43], s[16:17] offset:2048
	global_store_dwordx4 v176, v[44:47], s[16:17] offset:3072
	s_add_i32 s20, s20, s1
	s_cmp_lt_u32 s20, 0x10000
	s_cselect_b32 s3, s20, s0
	s_lshl_b32 s4, s3, 12
	s_add_u32 s6, s86, s4
	s_addc_u32 s7, s87, 0
	global_load_dwordx4 v[32:35], v176, s[6:7]
	global_load_dwordx4 v[36:39], v176, s[6:7] offset:1024
	global_load_dwordx4 v[40:43], v176, s[6:7] offset:2048
	global_load_dwordx4 v[44:47], v176, s[6:7] offset:3072
	s_branch .LNf_loop
.LNf_done:
.LBB0_2434:
	s_endpgm
